# adds attention mainloop loop-edge edits: back edge rotated in front of the loop-closing barrier (exit path has its own barrier copy), fragment-read address adds hoisted above both per-tile barriers, r
# speedup vs baseline: 1.0003x; 1.0003x over previous
; __device__ __forceinline__ void finishSM(f32x16& p0, f32x16& p1, float alpha, float& l_reg, bf16x8& pa0, bf16x8& pa1, bf16x8& pa2, bf16x8& pa3) {
;   for (int r = 0; r < 16; ++r) p1[r] = __builtin_amdgcn_exp2f(p1[r]);
;   float ps = 0; for (int r = 0; r < 16; ++r) ps += p0[r]; for (int r = 0; r < 16; ++r) ps += p1[r];
;   { auto rr = __builtin_amdgcn_permlane32_swap(__float_as_uint(ps), __float_as_uint(ps), false, false);
;     ps = __uint_as_float(rr[0]) + __uint_as_float(rr[1]); }
;   l_reg = l_reg * alpha + ps;
;     ...
;   PK4(p0, 0, pa0); PK4(p0, 8, pa1); PK4(p1, 0, pa2); PK4(p1, 8, pa3);
;     ...
; }
; __device__ __forceinline__ void qkt(f32x16& p0, f32x16& p1, const bf16* Ks, const bf16x8* qr, int r32, int hi) {
;   p0 = f32x16{}; p1 = f32x16{};
;   for (int d0 = 0; d0 < 8; ++d0) { int cb = (d0 * 16 + hi * 8) * 2;
;     bf16x8 b0 = *reinterpret_cast<const bf16x8*>((const char*)Ks + KSWZ(r32, cb));
;     bf16x8 b1 = *reinterpret_cast<const bf16x8*>((const char*)Ks + KSWZ(32 + r32, cb));
;     p0 = __builtin_amdgcn_mfma_f32_32x32x16_bf16(b0, qr[d0], p0, 0, 0, 0);
;     p1 = __builtin_amdgcn_mfma_f32_32x32x16_bf16(b1, qr[d0], p1, 0, 0, 0); }
; }
.Lmy_attn_top2:
	ds_read_b128 v[80:83], v84 offset:49152
	ds_read_b128 v[84:87], v84 offset:57344
	v_add_u32_e32 v202, s4, v215
	ds_read_b128 v[218:221], v202 offset:49152
	ds_read_b128 v[222:225], v202 offset:57344
	v_add_u32_e32 v202, s4, v214
	s_waitcnt lgkmcnt(3)
	v_mfma_f32_32x32x16_bf16 v[96:111], v[80:83], v[136:139], 0
	v_exp_f32_e32 v226, v71
	v_exp_f32_e32 v227, v72
	v_exp_f32_e32 v228, v73
	v_exp_f32_e32 v229, v74
	v_exp_f32_e32 v230, v75
	v_exp_f32_e32 v231, v76
	v_exp_f32_e32 v232, v77
	s_waitcnt lgkmcnt(2)
	v_mfma_f32_32x32x16_bf16 v[80:95], v[84:87], v[136:139], 0
	v_exp_f32_e32 v233, v78
	v_exp_f32_e32 v79, v79
	s_waitcnt lgkmcnt(1)
	v_mfma_f32_32x32x16_bf16 v[96:111], v[218:221], v[140:143], v[96:111]
	s_waitcnt lgkmcnt(0)
	v_mfma_f32_32x32x16_bf16 v[80:95], v[222:225], v[140:143], v[80:95]
	ds_read_b128 v[218:221], v202 offset:49152
	ds_read_b128 v[222:225], v202 offset:57344
	v_add_u32_e32 v202, s4, v211
	s_waitcnt lgkmcnt(1)
	v_mfma_f32_32x32x16_bf16 v[96:111], v[218:221], v[128:131], v[96:111]
	s_waitcnt lgkmcnt(0)
	v_mfma_f32_32x32x16_bf16 v[80:95], v[222:225], v[128:131], v[80:95]
	ds_read_b128 v[218:221], v202 offset:49152
	ds_read_b128 v[222:225], v202 offset:57344
	v_add_u32_e32 v202, s4, v209
	s_waitcnt lgkmcnt(1)
	v_mfma_f32_32x32x16_bf16 v[96:111], v[218:221], v[132:135], v[96:111]
	s_waitcnt lgkmcnt(0)
	v_mfma_f32_32x32x16_bf16 v[80:95], v[222:225], v[132:135], v[80:95]
	ds_read_b128 v[218:221], v202 offset:49152
	ds_read_b128 v[222:225], v202 offset:57344
	v_add_u32_e32 v202, s4, v206
	s_waitcnt lgkmcnt(1)
	v_mfma_f32_32x32x16_bf16 v[96:111], v[218:221], v[124:127], v[96:111]
	s_waitcnt lgkmcnt(0)
	v_mfma_f32_32x32x16_bf16 v[80:95], v[222:225], v[124:127], v[80:95]
	ds_read_b128 v[218:221], v202 offset:49152
	ds_read_b128 v[222:225], v202 offset:57344
	v_add_u32_e32 v202, s4, v207
	s_waitcnt lgkmcnt(1)
	v_mfma_f32_32x32x16_bf16 v[96:111], v[218:221], v[116:119], v[96:111]
	s_waitcnt lgkmcnt(0)
	v_mfma_f32_32x32x16_bf16 v[80:95], v[222:225], v[116:119], v[80:95]
	ds_read_b128 v[218:221], v202 offset:49152
	ds_read_b128 v[222:225], v202 offset:57344
	v_add_u32_e32 v202, s4, v212
	s_waitcnt lgkmcnt(1)
	v_mfma_f32_32x32x16_bf16 v[96:111], v[218:221], v[120:123], v[96:111]
	s_waitcnt lgkmcnt(0)
	v_mfma_f32_32x32x16_bf16 v[80:95], v[222:225], v[120:123], v[80:95]
	ds_read_b128 v[218:221], v202 offset:49152
	ds_read_b128 v[222:225], v202 offset:57344
	v_exp_f32_e32 v202, v64
	v_add_f32_e32 v64, 0, v173
	v_add_f32_e32 v64, v175, v64
	v_add_f32_e32 v64, v171, v64
	v_add_f32_e32 v64, v174, v64
	v_add_f32_e32 v64, v170, v64
	v_add_f32_e32 v64, v172, v64
	v_add_f32_e32 v64, v168, v64
	v_add_f32_e32 v64, v169, v64
	v_add_f32_e32 v64, v165, v64
	v_add_f32_e32 v64, v167, v64
	v_add_f32_e32 v64, v164, v64
	v_add_f32_e32 v64, v166, v64
	v_add_f32_e32 v64, v161, v64
	s_waitcnt lgkmcnt(1)
	v_mfma_f32_32x32x16_bf16 v[96:111], v[218:221], v[112:115], v[96:111]
	v_exp_f32_e32 v220, v65
	v_add_f32_e32 v64, v163, v64
	v_exp_f32_e32 v221, v66
	v_add_f32_e32 v64, v160, v64
	v_add_f32_e32 v64, v162, v64
	v_add_f32_e32 v64, v202, v64
	v_add_f32_e32 v64, v220, v64
	s_waitcnt lgkmcnt(0)
	v_mfma_f32_32x32x16_bf16 v[80:95], v[222:225], v[112:115], v[80:95]
	v_exp_f32_e32 v222, v67
	v_exp_f32_e32 v223, v68
	v_exp_f32_e32 v224, v69
	v_exp_f32_e32 v225, v70
	v_add_f32_e32 v64, v221, v64
	v_add_f32_e32 v64, v222, v64
	v_add_f32_e32 v64, v223, v64
	v_add_f32_e32 v64, v224, v64
	v_add_f32_e32 v64, v225, v64
	v_add_f32_e32 v64, v226, v64
	v_add_f32_e32 v64, v227, v64
	v_add_f32_e32 v64, v228, v64
	v_add_f32_e32 v64, v229, v64
	v_add_f32_e32 v64, v230, v64
	v_add_f32_e32 v64, v231, v64
	v_add_f32_e32 v64, v232, v64
	v_add_f32_e32 v64, v233, v64
	v_add_f32_e32 v218, v79, v64
	v_mov_b32_e32 v219, v218
	s_nop 1
	v_permlane32_swap_b32_e32 v218, v219
	v_cvt_pk_bf16_f32 v64, v173, v175
	v_cvt_pk_bf16_f32 v65, v171, v174
	v_cvt_pk_bf16_f32 v66, v170, v172
	v_cvt_pk_bf16_f32 v67, v168, v169
	v_cvt_pk_bf16_f32 v68, v165, v167
	v_cvt_pk_bf16_f32 v69, v164, v166
	v_cvt_pk_bf16_f32 v70, v161, v163
	v_cvt_pk_bf16_f32 v71, v160, v162
	v_cvt_pk_bf16_f32 v72, v202, v220
	v_cvt_pk_bf16_f32 v73, v221, v222
	v_cvt_pk_bf16_f32 v74, v223, v224
	v_cvt_pk_bf16_f32 v75, v225, v226
	v_cvt_pk_bf16_f32 v76, v227, v228
	v_cvt_pk_bf16_f32 v77, v229, v230
	v_cvt_pk_bf16_f32 v78, v231, v232
	v_cvt_pk_bf16_f32 v79, v233, v79
	s_nop 0
	v_permlane32_swap_b32_e32 v64, v66
	v_permlane32_swap_b32_e32 v65, v67
	v_permlane32_swap_b32_e32 v68, v70
	v_permlane32_swap_b32_e32 v69, v71
	v_permlane32_swap_b32_e32 v72, v74
	v_permlane32_swap_b32_e32 v73, v75
	v_permlane32_swap_b32_e32 v76, v78
	v_permlane32_swap_b32_e32 v77, v79
	s_movk_i32 s4, 0xa000
	v_add_co_u32_e32 v160, vcc, s4, v182
	s_movk_i32 s4, 0xc000
	s_nop 0
	v_addc_co_u32_e32 v161, vcc, -1, v183, vcc
	v_add_co_u32_e32 v164, vcc, s4, v182
	s_mov_b32 s4, 0xfeefa000
	s_nop 0
	v_addc_co_u32_e32 v165, vcc, -1, v183, vcc
	v_add_co_u32_e32 v168, vcc, s4, v182
	s_mov_b32 s4, 0xfeefc000
	s_nop 0
	v_addc_co_u32_e32 v169, vcc, -1, v183, vcc
	v_add_co_u32_e32 v172, vcc, s4, v182
	global_load_dwordx4 v[160:163], v[160:161], off
	s_nop 0
	global_load_dwordx4 v[164:167], v[164:165], off
	v_addc_co_u32_e32 v173, vcc, -1, v183, vcc
	global_load_dwordx4 v[168:171], v[168:169], off
	s_nop 0
	global_load_dwordx4 v[172:175], v[172:173], off
	v_add_u32_e32 v202, s9, v217
	ds_read_b64_tr_b16 v[220:221], v202 offset:0
	ds_read_b64_tr_b16 v[222:223], v202 offset:0x800
	ds_read_b64_tr_b16 v[224:225], v202 offset:0x1000
	ds_read_b64_tr_b16 v[226:227], v202 offset:0x1800
	ds_read_b64_tr_b16 v[228:229], v202 offset:0x2000
	ds_read_b64_tr_b16 v[230:231], v202 offset:0x2800
	ds_read_b64_tr_b16 v[232:233], v202 offset:0x3000
	ds_read_b64_tr_b16 v[234:235], v202 offset:0x3800
	s_waitcnt lgkmcnt(0)
; __device__ __forceinline__ void partialSM(f32x16& p0, f32x16& p1, float& m_reg, float& mn, float& alpha, bool bounded) {
;   constexpr float THRL = THR * 1.4426950408889634f;
;   if (bounded) { mn = m_reg; alpha = 1.f; }
;   else {
;     float pmax = p0[0]; for (int r = 1; r < 16; ++r) pmax = fmaxf(pmax, p0[r]); for (int r = 0; r < 16; ++r) pmax = fmaxf(pmax, p1[r]);
;     { auto rr = __builtin_amdgcn_permlane32_swap(__float_as_uint(pmax), __float_as_uint(pmax), false, false);
;       pmax = fmaxf(__uint_as_float(rr[0]), __uint_as_float(rr[1])); }
;     if (__builtin_expect(__all(pmax - m_reg <= THRL), 1)) { mn = m_reg; alpha = 1.f; }
;     else { mn = fmaxf(m_reg, pmax); alpha = __builtin_amdgcn_exp2f(m_reg - mn); m_reg = mn; }
;     for (int r = 0; r < 16; ++r) p0[r] -= mn; for (int r = 0; r < 16; ++r) p1[r] -= mn;
;   }
;   for (int r = 0; r < 16; ++r) p0[r] = __builtin_amdgcn_exp2f(p0[r]);
; }
; __device__ __forceinline__ void finishSM(f32x16& p0, f32x16& p1, float alpha, float& l_reg, bf16x8& pa0, bf16x8& pa1, bf16x8& pa2, bf16x8& pa3) {
;   for (int r = 0; r < 16; ++r) p1[r] = __builtin_amdgcn_exp2f(p1[r]);
;   float ps = 0; for (int r = 0; r < 16; ++r) ps += p0[r]; for (int r = 0; r < 16; ++r) ps += p1[r];
;   { auto rr = __builtin_amdgcn_permlane32_swap(__float_as_uint(ps), __float_as_uint(ps), false, false);
;     ps = __uint_as_float(rr[0]) + __uint_as_float(rr[1]); }
;   l_reg = l_reg * alpha + ps;
;     ...
;   PK4(p0, 0, pa0); PK4(p0, 8, pa1); PK4(p1, 0, pa2); PK4(p1, 8, pa3);
;     ...
; }
; __device__ __forceinline__ void qkt(f32x16& p0, f32x16& p1, const bf16* Ks, const bf16x8* qr, int r32, int hi) {
;   p0 = f32x16{}; p1 = f32x16{};
;   for (int d0 = 0; d0 < 8; ++d0) { int cb = (d0 * 16 + hi * 8) * 2;
;     bf16x8 b0 = *reinterpret_cast<const bf16x8*>((const char*)Ks + KSWZ(r32, cb));
;     bf16x8 b1 = *reinterpret_cast<const bf16x8*>((const char*)Ks + KSWZ(32 + r32, cb));
;     p0 = __builtin_amdgcn_mfma_f32_32x32x16_bf16(b0, qr[d0], p0, 0, 0, 0);
;     p1 = __builtin_amdgcn_mfma_f32_32x32x16_bf16(b1, qr[d0], p1, 0, 0, 0); }
; }
; __device__ __forceinline__ int v_st(int k, int c) { const int kk = (k & ~0xC) | ((k & 4) << 1) | ((k & 8) >> 1); return ((kk >> 3) * 4 + (c >> 5)) * 512 + ((kk & 7) * 32 + (c & 31)) * 2; }
	s_nop 0
	v_mfma_f32_32x32x16_bf16 v[0:15], v[64:67], v[220:223], v[0:15]
	ds_read_b64_tr_b16 v[220:221], v202 offset:0x200
	ds_read_b64_tr_b16 v[222:223], v202 offset:0xa00
	v_mfma_f32_32x32x16_bf16 v[0:15], v[68:71], v[224:227], v[0:15]
	ds_read_b64_tr_b16 v[224:225], v202 offset:0x1200
	ds_read_b64_tr_b16 v[226:227], v202 offset:0x1a00
	v_mfma_f32_32x32x16_bf16 v[0:15], v[72:75], v[228:231], v[0:15]
	ds_read_b64_tr_b16 v[228:229], v202 offset:0x2200
	ds_read_b64_tr_b16 v[230:231], v202 offset:0x2a00
	v_mfma_f32_32x32x16_bf16 v[0:15], v[76:79], v[232:235], v[0:15]
	ds_read_b64_tr_b16 v[232:233], v202 offset:0x3200
	ds_read_b64_tr_b16 v[234:235], v202 offset:0x3a00
	s_waitcnt lgkmcnt(0)
	v_mfma_f32_32x32x16_bf16 v[48:63], v[64:67], v[220:223], v[48:63]
	ds_read_b64_tr_b16 v[220:221], v202 offset:0x400
	ds_read_b64_tr_b16 v[222:223], v202 offset:0xc00
	v_mfma_f32_32x32x16_bf16 v[48:63], v[68:71], v[224:227], v[48:63]
	ds_read_b64_tr_b16 v[224:225], v202 offset:0x1400
	ds_read_b64_tr_b16 v[226:227], v202 offset:0x1c00
	v_mfma_f32_32x32x16_bf16 v[48:63], v[72:75], v[228:231], v[48:63]
	ds_read_b64_tr_b16 v[228:229], v202 offset:0x2400
	ds_read_b64_tr_b16 v[230:231], v202 offset:0x2c00
	v_mfma_f32_32x32x16_bf16 v[48:63], v[76:79], v[232:235], v[48:63]
	ds_read_b64_tr_b16 v[232:233], v202 offset:0x3400
	ds_read_b64_tr_b16 v[234:235], v202 offset:0x3c00
	s_waitcnt lgkmcnt(0)
	v_mfma_f32_32x32x16_bf16 v[32:47], v[64:67], v[220:223], v[32:47]
	ds_read_b64_tr_b16 v[220:221], v202 offset:0x600
	ds_read_b64_tr_b16 v[222:223], v202 offset:0xe00
	v_mfma_f32_32x32x16_bf16 v[32:47], v[68:71], v[224:227], v[32:47]
	ds_read_b64_tr_b16 v[224:225], v202 offset:0x1600
	ds_read_b64_tr_b16 v[226:227], v202 offset:0x1e00
	v_mfma_f32_32x32x16_bf16 v[32:47], v[72:75], v[228:231], v[32:47]
	ds_read_b64_tr_b16 v[228:229], v202 offset:0x2600
	ds_read_b64_tr_b16 v[230:231], v202 offset:0x2e00
	v_mfma_f32_32x32x16_bf16 v[32:47], v[76:79], v[232:235], v[32:47]
	ds_read_b64_tr_b16 v[232:233], v202 offset:0x3600
	ds_read_b64_tr_b16 v[234:235], v202 offset:0x3e00
	s_waitcnt lgkmcnt(0)
	v_mfma_f32_32x32x16_bf16 v[16:31], v[64:67], v[220:223], v[16:31]
	v_cndmask_b32_e64 v64, 0, 1, s[0:1]
	v_mov_b32_e32 v221, 1.0
	v_cmp_ne_u32_e64 s[42:43], 1, v64
	s_andn2_b64 vcc, exec, s[0:1]
	v_mfma_f32_32x32x16_bf16 v[16:31], v[68:71], v[224:227], v[16:31]
	v_mfma_f32_32x32x16_bf16 v[16:31], v[72:75], v[228:231], v[16:31]
	v_mfma_f32_32x32x16_bf16 v[16:31], v[76:79], v[232:235], v[16:31]
	s_cbranch_vccnz .LBB0_896
	v_max_f32_e32 v64, v97, v97
	v_max_f32_e32 v65, v96, v96
	v_max_f32_e32 v64, v65, v64
	v_max3_f32 v64, v64, v98, v99
	v_max3_f32 v64, v64, v100, v101
	v_max3_f32 v64, v64, v102, v103
	v_max3_f32 v64, v64, v104, v105
	v_max3_f32 v64, v64, v106, v107
	v_max3_f32 v64, v64, v108, v109
	v_max3_f32 v64, v64, v110, v111
	v_max3_f32 v64, v64, v80, v81
	v_max3_f32 v64, v64, v82, v83
	v_max3_f32 v64, v64, v84, v85
	v_max3_f32 v64, v64, v86, v87
	v_max3_f32 v64, v64, v88, v89
	v_max3_f32 v64, v64, v90, v91
	v_max3_f32 v64, v64, v92, v93
	v_max3_f32 v64, v64, v94, v95
	v_mov_b32_e32 v65, v64
	s_nop 1
	v_permlane32_swap_b32_e32 v64, v65
	v_max_f32_e32 v65, v65, v65
	v_max_f32_e32 v64, v64, v64
	v_max_f32_e32 v64, v64, v65
	v_sub_f32_e32 v65, v64, v201
	v_cmp_ge_f32_e32 vcc, s8, v65
	v_max_f32_e32 v65, v201, v201
	v_max_f32_e32 v64, v65, v64
	v_sub_f32_e32 v65, v201, v64
	v_exp_f32_e32 v65, v65
	s_cmp_eq_u64 vcc, exec
	s_cselect_b64 vcc, -1, 0
	v_cndmask_b32_e32 v201, v64, v201, vcc
	v_cndmask_b32_e64 v221, v65, 1.0, vcc
	v_sub_f32_e32 v111, v111, v201
	v_sub_f32_e32 v110, v110, v201
	v_sub_f32_e32 v109, v109, v201
	v_sub_f32_e32 v108, v108, v201
	v_sub_f32_e32 v107, v107, v201
	v_sub_f32_e32 v106, v106, v201
	v_sub_f32_e32 v105, v105, v201
	v_sub_f32_e32 v104, v104, v201
	v_sub_f32_e32 v103, v103, v201
	v_sub_f32_e32 v102, v102, v201
	v_sub_f32_e32 v101, v101, v201
	v_sub_f32_e32 v100, v100, v201
	v_sub_f32_e32 v99, v99, v201
	v_sub_f32_e32 v98, v98, v201
	v_sub_f32_e32 v97, v97, v201
	v_sub_f32_e32 v96, v96, v201
	v_sub_f32_e32 v95, v95, v201
	v_sub_f32_e32 v94, v94, v201
	v_sub_f32_e32 v93, v93, v201
	v_sub_f32_e32 v92, v92, v201
	v_sub_f32_e32 v91, v91, v201
	v_sub_f32_e32 v90, v90, v201
	v_sub_f32_e32 v89, v89, v201
	v_sub_f32_e32 v88, v88, v201
	v_sub_f32_e32 v87, v87, v201
	v_sub_f32_e32 v86, v86, v201
	v_sub_f32_e32 v85, v85, v201
	v_sub_f32_e32 v84, v84, v201
	v_sub_f32_e32 v83, v83, v201
	v_sub_f32_e32 v82, v82, v201
	v_sub_f32_e32 v81, v81, v201
	v_sub_f32_e32 v80, v80, v201
.LBB0_896:
	s_add_i32 s12, s11, 0
	v_add_u32_e32 v64, s12, v204
	s_waitcnt vmcnt(4)
	ds_write_b128 v64, v[144:147]
	v_add_u32_e32 v64, s12, v205
	ds_write_b128 v64, v[152:155]
	v_add_u32_e32 v64, s12, v208
	ds_write_b128 v64, v[148:151] offset:49152
	v_add_u32_e32 v64, s12, v210
	v_cmp_gt_f32_e32 vcc, 1.0, v221
	ds_write_b128 v64, v[156:159] offset:49152
	s_cbranch_vccz .LBB0_900
	s_and_saveexec_b64 s[4:5], s[40:41]
	ds_write_b32 v181, v221 offset:128
	s_or_b64 exec, exec, s[4:5]
	s_waitcnt lgkmcnt(0)
	v_add_u32_e32 v76, v179, v176
	ds_read_b128 v[64:67], v76 offset:224
	ds_read_b128 v[68:71], v76 offset:192
	ds_read_b128 v[72:75], v76 offset:160
	ds_read_b128 v[76:79], v76 offset:128
	s_waitcnt lgkmcnt(3)
	v_pk_mul_f32 v[12:13], v[12:13], v[64:65]
	s_waitcnt lgkmcnt(2)
	v_pk_mul_f32 v[8:9], v[8:9], v[68:69]
	s_waitcnt lgkmcnt(1)
	v_pk_mul_f32 v[4:5], v[4:5], v[72:73]
	v_pk_mul_f32 v[14:15], v[14:15], v[66:67]
	v_pk_mul_f32 v[10:11], v[10:11], v[70:71]
	v_pk_mul_f32 v[6:7], v[6:7], v[74:75]
	s_waitcnt lgkmcnt(0)
	v_pk_mul_f32 v[2:3], v[2:3], v[78:79]
	v_pk_mul_f32 v[0:1], v[0:1], v[76:77]
	v_pk_mul_f32 v[60:61], v[60:61], v[64:65]
	v_pk_mul_f32 v[56:57], v[56:57], v[68:69]
	v_pk_mul_f32 v[52:53], v[52:53], v[72:73]
	v_pk_mul_f32 v[62:63], v[62:63], v[66:67]
	v_pk_mul_f32 v[58:59], v[58:59], v[70:71]
	v_pk_mul_f32 v[54:55], v[54:55], v[74:75]
	v_pk_mul_f32 v[50:51], v[50:51], v[78:79]
	v_pk_mul_f32 v[48:49], v[48:49], v[76:77]
	v_pk_mul_f32 v[44:45], v[44:45], v[64:65]
	v_pk_mul_f32 v[40:41], v[40:41], v[68:69]
	v_pk_mul_f32 v[36:37], v[36:37], v[72:73]
	v_pk_mul_f32 v[46:47], v[46:47], v[66:67]
	v_pk_mul_f32 v[42:43], v[42:43], v[70:71]
	v_pk_mul_f32 v[38:39], v[38:39], v[74:75]
	v_pk_mul_f32 v[34:35], v[34:35], v[78:79]
	v_pk_mul_f32 v[32:33], v[32:33], v[76:77]
	v_pk_mul_f32 v[28:29], v[28:29], v[64:65]
	v_pk_mul_f32 v[24:25], v[24:25], v[68:69]
	v_pk_mul_f32 v[20:21], v[20:21], v[72:73]
	v_pk_mul_f32 v[30:31], v[30:31], v[66:67]
	v_pk_mul_f32 v[26:27], v[26:27], v[70:71]
	v_pk_mul_f32 v[22:23], v[22:23], v[74:75]
	v_pk_mul_f32 v[18:19], v[18:19], v[78:79]
	v_pk_mul_f32 v[16:17], v[16:17], v[76:77]
; #define SBAR() __builtin_amdgcn_sched_barrier(0)
; #define SLOAD(i, k0) do { sr_[i].vs0 = St::ld8(&Vh[(long)((k0) + sr) * LDK + sc]); sr_[i].vs1 = St::ld8(&Vh[(long)((k0) + 32 + sr) * LDK + sc]); \
;     sr_[i].ks0 = St::ld8(&Kh[(long)((k0) + sr) * LDK + sc]); sr_[i].ks1 = St::ld8(&Kh[(long)((k0) + 32 + sr) * LDK + sc]); } while (0)
; #define RESC(a) do { if (__any((a) < 1.f)) { if (hi == 0) al_l[r32] = (a); asm volatile("s_waitcnt lgkmcnt(0)" ::: "memory"); \
;     for (int d = 0; d < 4; ++d) for (int r = 0; r < 16; ++r) o[d][r] *= al_l[crow(r, hi)]; } } while (0)
; __device__ __forceinline__ void partialSM(f32x16& p0, f32x16& p1, float& m_reg, float& mn, float& alpha, bool bounded) {
;     ...
;   for (int r = 0; r < 16; ++r) p0[r] = __builtin_amdgcn_exp2f(p0[r]);
; }
; __device__ __forceinline__ void finishSM(f32x16& p0, f32x16& p1, float alpha, float& l_reg, bf16x8& pa0, bf16x8& pa1, bf16x8& pa2, bf16x8& pa3) {
;   for (int r = 0; r < 16; ++r) p1[r] = __builtin_amdgcn_exp2f(p1[r]);
;   float ps = 0; for (int r = 0; r < 16; ++r) ps += p0[r]; for (int r = 0; r < 16; ++r) ps += p1[r];
;   { auto rr = __builtin_amdgcn_permlane32_swap(__float_as_uint(ps), __float_as_uint(ps), false, false);
;     ps = __uint_as_float(rr[0]) + __uint_as_float(rr[1]); }
;   l_reg = l_reg * alpha + ps;
;     ...
;   PK4(p0, 0, pa0); PK4(p0, 8, pa1); PK4(p1, 0, pa2); PK4(p1, 8, pa3);
;     ...
; }
; __device__ __forceinline__ void qkt(f32x16& p0, f32x16& p1, const bf16* Ks, const bf16x8* qr, int r32, int hi) {
;   p0 = f32x16{}; p1 = f32x16{};
;   for (int d0 = 0; d0 < 8; ++d0) { int cb = (d0 * 16 + hi * 8) * 2;
;     bf16x8 b0 = *reinterpret_cast<const bf16x8*>((const char*)Ks + KSWZ(r32, cb));
;     bf16x8 b1 = *reinterpret_cast<const bf16x8*>((const char*)Ks + KSWZ(32 + r32, cb));
;     p0 = __builtin_amdgcn_mfma_f32_32x32x16_bf16(b0, qr[d0], p0, 0, 0, 0);
;     p1 = __builtin_amdgcn_mfma_f32_32x32x16_bf16(b1, qr[d0], p1, 0, 0, 0); }
; }
; template <typename TQ> ...
;     ...
;     RESC(alB); __syncthreads();
;     SBAR(); qkt(pA0, pA1, (bf16*)((char*)K_lds + o_nxt), qr, r32, hi);
;     finishSM(pB0, pB1, alB, l_reg, pa0, pa1, pa2, pa3); SBAR();
;     if (SDEPTH == 1 || j + 3 < NT) SLOAD(SE, (j + 1 + SDEPTH) * KVBLK); SBAR();
.LBB0_900:
	v_exp_f32_e32 v220, v96
	v_exp_f32_e32 v230, v97
	v_exp_f32_e32 v231, v98
	v_exp_f32_e32 v232, v99
	v_exp_f32_e32 v233, v100
	v_exp_f32_e32 v234, v101
	v_exp_f32_e32 v235, v102
	v_exp_f32_e32 v236, v103
	v_exp_f32_e32 v237, v104
	v_exp_f32_e32 v238, v105
	v_exp_f32_e32 v239, v106
	v_exp_f32_e32 v240, v107
	v_exp_f32_e32 v241, v108
	v_exp_f32_e32 v242, v109
	v_exp_f32_e32 v243, v110
	v_exp_f32_e32 v244, v111
	v_add_u32_e32 v68, s12, v213
	v_add_u32_e32 v226, s12, v215
	s_waitcnt lgkmcnt(0)
	s_barrier
	ds_read_b128 v[64:67], v68 offset:49152
	ds_read_b128 v[68:71], v68 offset:57344
	ds_read_b128 v[222:225], v226 offset:49152
	ds_read_b128 v[226:229], v226 offset:57344
	v_exp_f32_e32 v245, v86
	s_waitcnt lgkmcnt(3)
	v_mfma_f32_32x32x16_bf16 v[96:111], v[64:67], v[136:139], 0
	v_exp_f32_e32 v246, v87
	v_exp_f32_e32 v247, v88
	v_exp_f32_e32 v248, v89
	v_exp_f32_e32 v249, v90
	v_exp_f32_e32 v250, v91
	v_exp_f32_e32 v251, v92
	v_exp_f32_e32 v252, v93
	s_waitcnt lgkmcnt(2)
	v_mfma_f32_32x32x16_bf16 v[64:79], v[68:71], v[136:139], 0
	v_exp_f32_e32 v194, v94
	v_exp_f32_e32 v95, v95
	s_waitcnt lgkmcnt(1)
	v_mfma_f32_32x32x16_bf16 v[96:111], v[222:225], v[140:143], v[96:111]
	s_waitcnt lgkmcnt(0)
	v_mfma_f32_32x32x16_bf16 v[64:79], v[226:229], v[140:143], v[64:79]
	v_add_u32_e32 v226, s12, v214
	ds_read_b128 v[222:225], v226 offset:49152
	ds_read_b128 v[226:229], v226 offset:57344
	s_waitcnt lgkmcnt(1)
	v_mfma_f32_32x32x16_bf16 v[96:111], v[222:225], v[128:131], v[96:111]
	s_waitcnt lgkmcnt(0)
	v_mfma_f32_32x32x16_bf16 v[64:79], v[226:229], v[128:131], v[64:79]
	v_add_u32_e32 v226, s12, v211
	ds_read_b128 v[222:225], v226 offset:49152
	ds_read_b128 v[226:229], v226 offset:57344
	s_waitcnt lgkmcnt(1)
	v_mfma_f32_32x32x16_bf16 v[96:111], v[222:225], v[132:135], v[96:111]
	s_waitcnt lgkmcnt(0)
	v_mfma_f32_32x32x16_bf16 v[64:79], v[226:229], v[132:135], v[64:79]
	v_add_u32_e32 v226, s12, v209
	ds_read_b128 v[222:225], v226 offset:49152
	ds_read_b128 v[226:229], v226 offset:57344
	s_waitcnt lgkmcnt(1)
	v_mfma_f32_32x32x16_bf16 v[96:111], v[222:225], v[124:127], v[96:111]
	s_waitcnt lgkmcnt(0)
	v_mfma_f32_32x32x16_bf16 v[64:79], v[226:229], v[124:127], v[64:79]
	v_add_u32_e32 v226, s12, v206
	ds_read_b128 v[222:225], v226 offset:49152
	ds_read_b128 v[226:229], v226 offset:57344
	s_waitcnt lgkmcnt(1)
	v_mfma_f32_32x32x16_bf16 v[96:111], v[222:225], v[116:119], v[96:111]
	s_waitcnt lgkmcnt(0)
	v_mfma_f32_32x32x16_bf16 v[64:79], v[226:229], v[116:119], v[64:79]
	v_add_u32_e32 v226, s12, v207
	ds_read_b128 v[222:225], v226 offset:49152
	ds_read_b128 v[226:229], v226 offset:57344
	s_waitcnt lgkmcnt(1)
	v_mfma_f32_32x32x16_bf16 v[96:111], v[222:225], v[120:123], v[96:111]
	s_waitcnt lgkmcnt(0)
	v_mfma_f32_32x32x16_bf16 v[64:79], v[226:229], v[120:123], v[64:79]
	v_add_u32_e32 v226, s12, v212
	ds_read_b128 v[222:225], v226 offset:49152
	ds_read_b128 v[226:229], v226 offset:57344
	s_waitcnt lgkmcnt(1)
	v_mfma_f32_32x32x16_bf16 v[96:111], v[222:225], v[112:115], v[96:111]
	v_exp_f32_e32 v224, v80
	v_add_f32_e32 v80, 0, v220
	v_add_f32_e32 v80, v230, v80
	v_add_f32_e32 v80, v231, v80
	v_add_f32_e32 v80, v232, v80
	v_add_f32_e32 v80, v233, v80
	v_add_f32_e32 v80, v234, v80
	v_add_f32_e32 v80, v235, v80
	v_add_f32_e32 v80, v236, v80
	v_add_f32_e32 v80, v237, v80
	v_add_f32_e32 v80, v238, v80
	v_add_f32_e32 v80, v239, v80
	v_add_f32_e32 v80, v240, v80
	v_add_f32_e32 v80, v241, v80
	v_exp_f32_e32 v225, v81
	v_add_f32_e32 v80, v242, v80
	s_waitcnt lgkmcnt(0)
	v_mfma_f32_32x32x16_bf16 v[64:79], v[226:229], v[112:115], v[64:79]
	v_exp_f32_e32 v226, v82
	v_add_f32_e32 v80, v243, v80
	v_exp_f32_e32 v227, v83
	v_add_f32_e32 v80, v244, v80
	v_exp_f32_e32 v228, v84
	v_add_f32_e32 v80, v224, v80
	v_exp_f32_e32 v229, v85
	v_add_f32_e32 v80, v225, v80
	v_add_f32_e32 v80, v226, v80
	v_add_f32_e32 v80, v227, v80
	v_add_f32_e32 v80, v228, v80
	v_add_f32_e32 v80, v229, v80
	v_add_f32_e32 v80, v245, v80
	v_add_f32_e32 v80, v246, v80
	v_add_f32_e32 v80, v247, v80
	v_add_f32_e32 v80, v248, v80
	v_add_f32_e32 v80, v249, v80
	v_add_f32_e32 v80, v250, v80
	v_add_f32_e32 v80, v251, v80
	v_add_f32_e32 v80, v252, v80
	v_add_f32_e32 v80, v194, v80
	v_add_f32_e32 v222, v95, v80
	v_mov_b32_e32 v223, v222
	v_cvt_pk_bf16_f32 v80, v220, v230
	v_cvt_pk_bf16_f32 v81, v231, v232
	v_cvt_pk_bf16_f32 v82, v233, v234
	v_cvt_pk_bf16_f32 v83, v235, v236
	v_cvt_pk_bf16_f32 v84, v237, v238
	v_cvt_pk_bf16_f32 v85, v239, v240
	v_cvt_pk_bf16_f32 v86, v241, v242
	v_cvt_pk_bf16_f32 v87, v243, v244
	v_cvt_pk_bf16_f32 v88, v224, v225
	v_cvt_pk_bf16_f32 v89, v226, v227
	v_cvt_pk_bf16_f32 v90, v228, v229
	v_cvt_pk_bf16_f32 v91, v245, v246
	v_cvt_pk_bf16_f32 v92, v247, v248
	v_cvt_pk_bf16_f32 v93, v249, v250
	v_cvt_pk_bf16_f32 v94, v251, v252
	v_cvt_pk_bf16_f32 v95, v194, v95
	s_nop 1
	v_permlane32_swap_b32_e32 v222, v223
	v_permlane32_swap_b32_e32 v80, v82
	v_permlane32_swap_b32_e32 v81, v83
	v_permlane32_swap_b32_e32 v84, v86
	v_permlane32_swap_b32_e32 v85, v87
	v_permlane32_swap_b32_e32 v88, v90
	v_permlane32_swap_b32_e32 v89, v91
	v_permlane32_swap_b32_e32 v92, v94
	v_permlane32_swap_b32_e32 v93, v95
	s_cmpk_gt_u32 s3, 0x80
	s_cselect_b64 s[34:35], -1, 0
	s_and_b64 vcc, exec, s[34:35]
	s_cbranch_vccnz .LBB0_902
	v_add_co_u32_e32 v144, vcc, 0xffffe000, v182
	s_nop 1
	v_addc_co_u32_e32 v145, vcc, -1, v183, vcc
	v_add_co_u32_e32 v148, vcc, 0xfeefe000, v182
	s_nop 1
	v_addc_co_u32_e32 v149, vcc, -1, v183, vcc
	v_add_co_u32_e32 v156, vcc, 0xfef00000, v182
	global_load_dwordx4 v[144:147], v[144:145], off
	s_nop 0
	global_load_dwordx4 v[148:151], v[148:149], off
	v_addc_co_u32_e32 v157, vcc, -1, v183, vcc
	global_load_dwordx4 v[152:155], v[182:183], off
	s_nop 0
	global_load_dwordx4 v[156:159], v[156:157], off

; #define SBAR() __builtin_amdgcn_sched_barrier(0)
; #define SLOAD(i, k0) do { sr_[i].vs0 = St::ld8(&Vh[(long)((k0) + sr) * LDK + sc]); sr_[i].vs1 = St::ld8(&Vh[(long)((k0) + 32 + sr) * LDK + sc]); \
;     sr_[i].ks0 = St::ld8(&Kh[(long)((k0) + sr) * LDK + sc]); sr_[i].ks1 = St::ld8(&Kh[(long)((k0) + 32 + sr) * LDK + sc]); } while (0)
; #define SWRITE(bo, i) do { *(bf16x8*)((char*)V_lds + (bo) + vst0) = St::tobf(sr_[i].vs0);            \
;     *(bf16x8*)((char*)V_lds + (bo) + vst1) = St::tobf(sr_[i].vs1); int kc = sc * 2;               \
;     *(bf16x8*)((char*)K_lds + (bo) + KSWZ(sr, kc)) = St::tobf(sr_[i].ks0);                       \
;     *(bf16x8*)((char*)K_lds + (bo) + KSWZ(32 + sr, kc)) = St::tobf(sr_[i].ks1); } while (0)
; #define SWAIT() do { if constexpr (SDEPTH == 2) asm volatile("s_waitcnt vmcnt(4)" ::: "memory"); else asm volatile("s_waitcnt vmcnt(0)" ::: "memory"); } while (0)
; #define RESC(a) do { if (__any((a) < 1.f)) { if (hi == 0) al_l[r32] = (a); asm volatile("s_waitcnt lgkmcnt(0)" ::: "memory"); \
;     for (int d = 0; d < 4; ++d) for (int r = 0; r < 16; ++r) o[d][r] *= al_l[crow(r, hi)]; } } while (0)
; template <typename TQ> ...
;     ...
;   for (int j = 1; j + 1 < NT; j += 2) {
;     SBAR(); qkt(pB0, pB1, (bf16*)((char*)K_lds + o_cur), qr, r32, hi);
;     finishSM(pA0, pA1, alA, l_reg, pa0, pa1, pa2, pa3); SBAR();
;     SLOAD(SO, (j + SDEPTH) * KVBLK); SBAR();
;     pv_d0(o, vb0 + o_prev, pa0, pa1, pa2, pa3); partialSM(pB0, pB1, m_reg, mnB, alB, bounded);
;     SWAIT(); SWRITE(o_nxt, SE);
;     RESC(alB); __syncthreads();
;     SBAR(); qkt(pA0, pA1, (bf16*)((char*)K_lds + o_nxt), qr, r32, hi);
;     finishSM(pB0, pB1, alB, l_reg, pa0, pa1, pa2, pa3); SBAR();
;     if (SDEPTH == 1 || j + 3 < NT) SLOAD(SE, (j + 1 + SDEPTH) * KVBLK); SBAR();
;     pv_d0(o, vb0 + o_cur, pa0, pa1, pa2, pa3); partialSM(pA0, pA1, m_reg, mnA, alA, bounded);
;     SWAIT(); SWRITE(o_prev, SO);
;     RESC(alA); __syncthreads();
;     { const int t = o_prev; o_prev = o_nxt; o_nxt = o_cur; o_cur = t; }
;   }
.LBB0_908:
	v_exp_f32_e32 v173, v96
	v_exp_f32_e32 v175, v97
	v_exp_f32_e32 v171, v98
	v_exp_f32_e32 v174, v99
	v_exp_f32_e32 v170, v100
	v_exp_f32_e32 v172, v101
	v_exp_f32_e32 v168, v102
	v_exp_f32_e32 v169, v103
	v_exp_f32_e32 v165, v104
	v_exp_f32_e32 v167, v105
	v_exp_f32_e32 v164, v106
	v_exp_f32_e32 v166, v107
	v_exp_f32_e32 v161, v108
	v_exp_f32_e32 v163, v109
	v_exp_f32_e32 v160, v110
	v_exp_f32_e32 v162, v111
	v_add_f32_e32 v80, v218, v219
	v_fmac_f32_e32 v80, v203, v200
	v_add_f32_e32 v200, v222, v223
	v_fmac_f32_e32 v200, v80, v221
	s_add_i32 s3, s3, 2
	v_lshl_add_u64 v[182:183], v[182:183], 0, s[74:75]
	s_and_b64 vcc, exec, s[34:35]
	s_cbranch_vccnz .Lmy_attn_exit
	s_mov_b32 s4, s10
	s_mov_b32 s10, s9
	s_mov_b32 s9, s11
	v_mov_b32_e32 v203, v220
	s_mov_b32 s11, s4
	s_add_i32 s4, s10, 0
	v_add_u32_e32 v84, s4, v213
	s_waitcnt lgkmcnt(0)
	s_barrier
	s_branch .Lmy_attn_top2
.Lmy_attn_exit:
	s_waitcnt lgkmcnt(0)
	s_barrier
